# U0 lowered to the minimum 11264 items up front (first three slots 13696 items each)
# speedup vs baseline: 1.0387x; 1.0031x over previous
.LBB0_5:
	s_or_b64 exec, exec, s[4:5]
	s_lshl_b32 s81, s69, 3
	s_lshl_b32 s88, s76, 3
	s_mov_b32 s101, s81
	s_mov_b32 s98, s88
	s_mov_b32 s100, 0
	s_mov_b32 s99, 0x2c00
	s_cmpk_eq_u32 s76, 0x100
	s_cbranch_scc1 .Lconv_entry
	s_mov_b32 s99, 0x14100

.LBB0_143:
	v_readlane_b32 s98, v254, 35
	v_readlane_b32 s100, v254, 45
	s_cmpk_lt_u32 s98, 0x80
	s_cbranch_scc1 .Lslot_a_done
	s_cmp_lg_u64 s[10:11], 0
	s_cbranch_scc0 .Lsa_f1
	s_cmp_eq_u32 s100, 0
	s_cbranch_scc0 .Lsa_f0l1
	s_mov_b32 s101, 0x2c00
	s_mov_b32 s99, 0x6180
	s_branch .Lsa_go

.Lsa_f1:
	s_cmp_eq_u32 s100, 0
	s_cbranch_scc0 .Lsa_f1l1
	s_mov_b32 s101, 0x9700
	s_mov_b32 s99, 0xcc80
	s_branch .Lsa_go

.LBB0_362:
	v_readlane_b32 s98, v254, 35
	v_readlane_b32 s100, v254, 45
	s_cmpk_lt_u32 s98, 0x80
	s_cbranch_scc1 .Lslot_w_done
	s_cmp_eq_u32 s100, 0
	s_cbranch_scc0 .Lsw_f0l1
	s_mov_b32 s101, 0x6180
	s_mov_b32 s99, 0x9700
	s_branch .Lsw_go
